# A-layer in-projection: meta-row GEMM tasks dealt only to the work-groups with one tile fewer (WGs 112-127 no longer carry a task after their fifth tile)
# speedup vs baseline: 1.0051x; 1.0047x over previous
; #define LAS __attribute__((address_space(3)))
;     DI bool next(int i, Unit& u) const {
;         const long L = (long)i * G + c; if (L >= nwg) return false;
;         int wgid = (int)L; { const int q = nwg / NXCD, r = nwg % NXCD, xcd = wgid % NXCD, off = wgid / NXCD; wgid = (xcd < r ? xcd * (q + 1) : r * (q + 1) + (xcd - r) * q) + off; }
; template <bool TILED_IN>
; DI void meta_gemm(const bf16_t* am, int lda, const bf16_t* Wt, int N, bf16_t* zo, int ldzo, int nt, LAS unsigned char* lds, int bid, int G, int wave, int lane) {
;     const int ntasks = N / 16, r = lane & 15, q = lane >> 4, kq = wave & 3;
;     LAS f32x4* part = (LAS f32x4*)lds;
;     for (int t0 = 2 * (G - 1 - bid); t0 < ntasks; t0 += 2 * G) {
;         const int task = t0 + (wave >> 2), n0 = task * 16;
.LBB0_67:
	s_cmpk_lg_u32 s24, 0x1200
	s_cbranch_scc1 .Lmeta_deal_done
	s_movk_i32 s5, 0x480
.Lmeta_mod:
	s_cmp_lt_u32 s5, s10
	s_cbranch_scc1 .Lmeta_mod_done
	s_sub_u32 s5, s5, s10
	s_branch .Lmeta_mod
.Lmeta_mod_done:
	s_cmp_eq_u32 s5, 0
	s_cbranch_scc1 .Lmeta_deal_done
	s_cmp_lt_u32 s11, s5
	s_cbranch_scc1 .LBB0_74
	s_sub_u32 s11, s11, s5
	s_sub_u32 s10, s10, s5
